# ffn-up K-loop shifted by one 4-byte nop (loop head 8-byte aligned)
# speedup vs baseline: 1.0016x; 1.0016x over previous
.LBB0_91:
	s_ashr_i32 s53, s52, 31
	s_lshl_b64 s[10:11], s[52:53], 19
	s_add_u32 s54, s68, s10
	s_addc_u32 s55, s69, s11
	s_and_b64 s[10:11], s[40:41], exec
	s_cselect_b32 s5, s55, s7
	s_cselect_b32 s24, s54, s6
	s_ashr_i32 s51, s50, 31
	s_lshl_b64 s[10:11], s[50:51], 19
	s_add_u32 s56, s15, s10
	s_addc_u32 s57, s26, s11
	s_and_b64 s[10:11], s[40:41], exec
	s_cselect_b32 s47, s57, s9
	s_cselect_b32 s51, s56, s8
	s_add_u32 s6, s6, 0x40080
	s_addc_u32 s7, s7, 0
	s_add_u32 s53, s8, 0x100
	v_mov_b32_e32 v0, 0
	v_mov_b32_e32 v251, 0x260
	v_mov_b32_e32 v224, 0x3e124925
	v_mov_b32_e32 v223, 0x3e2aaaab
	v_mov_b32_e32 v222, 0x3e4ccccd
	v_mov_b32_e32 v221, 0x3e800000
	v_mov_b32_e32 v220, 0x3eaaaaab
	s_addc_u32 s58, s9, 0
	s_mov_b32 s59, -2
	v_mov_b32_e32 v1, v0
	v_mov_b32_e32 v2, v0
	v_mov_b32_e32 v3, v0
	v_mov_b32_e32 v4, v0
	v_mov_b32_e32 v5, v0
	v_mov_b32_e32 v6, v0
	v_mov_b32_e32 v7, v0
	v_mov_b32_e32 v16, v0
	v_mov_b32_e32 v17, v0
	v_mov_b32_e32 v18, v0
	v_mov_b32_e32 v19, v0
	v_mov_b32_e32 v20, v0
	v_mov_b32_e32 v21, v0
	v_mov_b32_e32 v22, v0
	v_mov_b32_e32 v23, v0
	v_mov_b32_e32 v32, v0
	v_mov_b32_e32 v33, v0
	v_mov_b32_e32 v34, v0
	v_mov_b32_e32 v35, v0
	v_mov_b32_e32 v36, v0
	v_mov_b32_e32 v37, v0
	v_mov_b32_e32 v38, v0
	v_mov_b32_e32 v39, v0
	v_mov_b32_e32 v48, v0
	v_mov_b32_e32 v49, v0
	v_mov_b32_e32 v50, v0
	v_mov_b32_e32 v51, v0
	v_mov_b32_e32 v52, v0
	v_mov_b32_e32 v53, v0
	v_mov_b32_e32 v54, v0
	v_mov_b32_e32 v55, v0
	v_mov_b32_e32 v8, v0
	v_mov_b32_e32 v9, v0
	v_mov_b32_e32 v10, v0
	v_mov_b32_e32 v11, v0
	v_mov_b32_e32 v12, v0
	v_mov_b32_e32 v13, v0
	v_mov_b32_e32 v14, v0
	v_mov_b32_e32 v15, v0
	v_mov_b32_e32 v24, v0
	v_mov_b32_e32 v25, v0
	v_mov_b32_e32 v26, v0
	v_mov_b32_e32 v27, v0
	v_mov_b32_e32 v28, v0
	v_mov_b32_e32 v29, v0
	v_mov_b32_e32 v30, v0
	v_mov_b32_e32 v31, v0
	v_mov_b32_e32 v40, v0
	v_mov_b32_e32 v41, v0
	v_mov_b32_e32 v42, v0
	v_mov_b32_e32 v43, v0
	v_mov_b32_e32 v44, v0
	v_mov_b32_e32 v45, v0
	v_mov_b32_e32 v46, v0
	v_mov_b32_e32 v47, v0
	v_mov_b32_e32 v56, v0
	v_mov_b32_e32 v57, v0
	v_mov_b32_e32 v58, v0
	v_mov_b32_e32 v59, v0
	v_mov_b32_e32 v60, v0
	v_mov_b32_e32 v61, v0
	v_mov_b32_e32 v62, v0
	v_mov_b32_e32 v63, v0
	v_mov_b32_e32 v64, v0
	v_mov_b32_e32 v65, v0
	v_mov_b32_e32 v66, v0
	v_mov_b32_e32 v67, v0
	v_mov_b32_e32 v68, v0
	v_mov_b32_e32 v69, v0
	v_mov_b32_e32 v70, v0
	v_mov_b32_e32 v71, v0
	v_mov_b32_e32 v80, v0
	v_mov_b32_e32 v81, v0
	v_mov_b32_e32 v82, v0
	v_mov_b32_e32 v83, v0
	v_mov_b32_e32 v84, v0
	v_mov_b32_e32 v85, v0
	v_mov_b32_e32 v86, v0
	v_mov_b32_e32 v87, v0
	v_mov_b32_e32 v96, v0
	v_mov_b32_e32 v97, v0
	v_mov_b32_e32 v98, v0
	v_mov_b32_e32 v99, v0
	v_mov_b32_e32 v100, v0
	v_mov_b32_e32 v101, v0
	v_mov_b32_e32 v102, v0
	v_mov_b32_e32 v103, v0
	v_mov_b32_e32 v112, v0
	v_mov_b32_e32 v113, v0
	v_mov_b32_e32 v114, v0
	v_mov_b32_e32 v115, v0
	v_mov_b32_e32 v116, v0
	v_mov_b32_e32 v117, v0
	v_mov_b32_e32 v118, v0
	v_mov_b32_e32 v119, v0
	v_mov_b32_e32 v72, v0
	v_mov_b32_e32 v73, v0
	v_mov_b32_e32 v74, v0
	v_mov_b32_e32 v75, v0
	v_mov_b32_e32 v76, v0
	v_mov_b32_e32 v77, v0
	v_mov_b32_e32 v78, v0
	v_mov_b32_e32 v79, v0
	v_mov_b32_e32 v88, v0
	v_mov_b32_e32 v89, v0
	v_mov_b32_e32 v90, v0
	v_mov_b32_e32 v91, v0
	v_mov_b32_e32 v92, v0
	v_mov_b32_e32 v93, v0
	v_mov_b32_e32 v94, v0
	v_mov_b32_e32 v95, v0
	v_mov_b32_e32 v104, v0
	v_mov_b32_e32 v105, v0
	v_mov_b32_e32 v106, v0
	v_mov_b32_e32 v107, v0
	v_mov_b32_e32 v108, v0
	v_mov_b32_e32 v109, v0
	v_mov_b32_e32 v110, v0
	v_mov_b32_e32 v111, v0
	v_mov_b32_e32 v120, v0
	v_mov_b32_e32 v121, v0
	v_mov_b32_e32 v122, v0
	v_mov_b32_e32 v123, v0
	v_mov_b32_e32 v124, v0
	v_mov_b32_e32 v125, v0
	v_mov_b32_e32 v126, v0
	v_mov_b32_e32 v127, v0
	s_nop 0
